# SSD unit: logical wave ids permuted so SIMD pairs carry equal diagonal-block work
# baseline (speedup 1.0000x reference)
.LBB0_960:
	s_mov_b64 s[22:23], s[90:91]
	v_mov_b32_e32 v144, v214
	v_lshrrev_b32_e32 v1, 6, v144
	v_sub_u32_e32 v2, 11, v1
	v_cmp_gt_u32_e32 vcc, 4, v1
	s_nop 1
	v_cndmask_b32_e32 v1, v2, v1, vcc
	v_and_b32_e32 v144, 63, v144
	v_lshl_or_b32 v144, v1, 6, v144
	s_movk_i32 s0, 0x440
	v_mov_b32_e32 v0, v113
	v_readfirstlane_b32 s60, v144
	v_cmp_gt_i32_e32 vcc, s0, v144
	s_and_saveexec_b64 s[0:1], vcc
	s_cbranch_execz .LBB0_963
	v_readlane_b32 s2, v254, 15
	s_waitcnt lgkmcnt(0)
	v_mov_b32_e32 v1, v0
	v_mov_b32_e32 v2, v0
	v_mov_b32_e32 v3, v0
	v_add_u32_e32 v4, 0xfffffe00, v144
	v_lshl_add_u32 v5, v144, 4, s2
	s_mov_b64 s[2:3], 0
